# tail units; producer waves drain their stores at the end of sample-panel tile epilogues, wave0 write-back at unit 2, flag at unit 3
# speedup vs baseline: 1.0015x; 1.0015x over previous
.Lsd3_x:
	v_mul_f32_e32 v157, 0xbfb8aa3b, v124
	v_exp_f32_e32 v157, v157
	v_mul_f32_e32 v160, 0xbfb8aa3b, v125
	v_exp_f32_e32 v160, v160
	v_lshl_or_b32 v148, s37, 7, v152
	v_add_f32_e32 v157, 1.0, v157
	v_rcp_f32_e32 v157, v157
	v_add_f32_e32 v160, 1.0, v160
	v_rcp_f32_e32 v160, v160
	v_lshl_add_u32 v156, s58, 8, v150
	v_mul_f32_e32 v124, v124, v157
	v_mul_f32_e32 v116, v116, v124
	v_mul_f32_e32 v124, v125, v160
	v_mul_f32_e32 v125, 0xbfb8aa3b, v126
	v_exp_f32_e32 v125, v125
	v_mul_f32_e32 v157, 0xbfb8aa3b, v127
	v_exp_f32_e32 v157, v157
	v_mul_f32_e32 v117, v117, v124
	v_add_f32_e32 v124, 1.0, v125
	v_rcp_f32_e32 v124, v124
	v_add_f32_e32 v125, 1.0, v157
	v_rcp_f32_e32 v125, v125
	v_cvt_pk_bf16_f32 v116, v116, v117
	v_mul_f32_e32 v117, v126, v124
	v_mul_f32_e32 v124, 0xbfb8aa3b, v120
	v_exp_f32_e32 v124, v124
	v_mul_f32_e32 v117, v118, v117
	v_mul_f32_e32 v118, v127, v125
	v_mul_f32_e32 v125, 0xbfb8aa3b, v121
	v_exp_f32_e32 v125, v125
	v_mul_f32_e32 v118, v119, v118
	v_add_f32_e32 v119, 1.0, v124
	v_rcp_f32_e32 v119, v119
	v_add_f32_e32 v124, 1.0, v125
	v_rcp_f32_e32 v124, v124
	v_cvt_pk_bf16_f32 v117, v117, v118
	v_mul_f32_e32 v118, v120, v119
	v_mul_f32_e32 v119, 0xbfb8aa3b, v122
	v_exp_f32_e32 v119, v119
	v_mul_f32_e32 v120, 0xbfb8aa3b, v123
	v_exp_f32_e32 v120, v120
	v_mul_f32_e32 v112, v112, v118
	v_mul_f32_e32 v118, v121, v124
	v_mul_f32_e32 v113, v113, v118
	v_add_f32_e32 v118, 1.0, v119
	v_rcp_f32_e32 v119, v118
	v_add_f32_e32 v118, 1.0, v120
	v_rcp_f32_e32 v120, v118
	v_cvt_pk_bf16_f32 v118, v112, v113
	v_mul_f32_e32 v112, v122, v119
	v_mul_f32_e32 v112, v114, v112
	v_mul_f32_e32 v113, v123, v120
	v_mul_f32_e32 v113, v115, v113
	v_cvt_pk_bf16_f32 v119, v112, v113
	v_mul_f32_e32 v113, 0xbfb8aa3b, v108
	v_exp_f32_e32 v114, v113
	v_mul_f32_e32 v113, 0xbfb8aa3b, v109
	v_exp_f32_e32 v115, v113
	v_ashrrev_i32_e32 v149, 31, v148
	v_add_f32_e32 v114, 1.0, v114
	v_rcp_f32_e32 v114, v114
	v_add_f32_e32 v115, 1.0, v115
	v_rcp_f32_e32 v115, v115
	v_mov_b64_e32 v[146:147], s[18:19]
	v_mul_f32_e32 v108, v108, v114
	v_mul_f32_e32 v100, v100, v108
	v_mul_f32_e32 v108, v109, v115
	v_mul_f32_e32 v109, 0xbfb8aa3b, v110
	v_exp_f32_e32 v109, v109
	v_mul_f32_e32 v114, 0xbfb8aa3b, v111
	v_exp_f32_e32 v114, v114
	v_mul_f32_e32 v101, v101, v108
	v_add_f32_e32 v108, 1.0, v109
	v_rcp_f32_e32 v108, v108
	v_mad_i64_i32 v[158:159], s[6:7], v156, s36, v[146:147]
	v_lshlrev_b64 v[148:149], 1, v[148:149]
	v_lshl_add_u64 v[158:159], v[158:159], 0, v[148:149]
	v_add_f32_e32 v109, 1.0, v114
	global_store_dwordx4 v[158:159], v[116:119], off
	v_rcp_f32_e32 v109, v109
	v_cvt_pk_bf16_f32 v100, v100, v101
	v_mul_f32_e32 v101, v110, v108
	v_mul_f32_e32 v108, 0xbfb8aa3b, v104
	v_exp_f32_e32 v108, v108
	v_mul_f32_e32 v101, v102, v101
	v_mul_f32_e32 v102, v111, v109
	v_mul_f32_e32 v109, 0xbfb8aa3b, v105
	v_exp_f32_e32 v109, v109
	v_mul_f32_e32 v102, v103, v102
	v_add_f32_e32 v103, 1.0, v108
	v_rcp_f32_e32 v103, v103
	v_add_f32_e32 v108, 1.0, v109
	v_rcp_f32_e32 v108, v108
	v_cvt_pk_bf16_f32 v101, v101, v102
	v_mul_f32_e32 v102, v104, v103
	v_mul_f32_e32 v103, 0xbfb8aa3b, v106
	v_exp_f32_e32 v103, v103
	v_mul_f32_e32 v104, 0xbfb8aa3b, v107
	v_exp_f32_e32 v104, v104
	v_mul_f32_e32 v96, v96, v102
	v_mul_f32_e32 v102, v105, v108
	v_mul_f32_e32 v97, v97, v102
	v_add_f32_e32 v102, 1.0, v103
	v_rcp_f32_e32 v103, v102
	v_add_f32_e32 v102, 1.0, v104
	v_rcp_f32_e32 v104, v102
	v_cvt_pk_bf16_f32 v102, v96, v97
	v_mul_f32_e32 v96, v106, v103
	v_mul_f32_e32 v96, v98, v96
	v_mul_f32_e32 v97, v107, v104
	v_mul_f32_e32 v97, v99, v97
	v_cvt_pk_bf16_f32 v103, v96, v97
	v_mul_f32_e32 v97, 0xbfb8aa3b, v92
	v_exp_f32_e32 v98, v97
	v_mul_f32_e32 v97, 0xbfb8aa3b, v93
	v_exp_f32_e32 v99, v97
	v_or_b32_e32 v112, 16, v156
	v_add_f32_e32 v98, 1.0, v98
	v_rcp_f32_e32 v98, v98
	v_add_f32_e32 v99, 1.0, v99
	v_rcp_f32_e32 v99, v99
	v_mad_i64_i32 v[112:113], s[6:7], v112, s36, v[146:147]
	v_mul_f32_e32 v92, v92, v98
	v_mul_f32_e32 v84, v84, v92
	v_mul_f32_e32 v92, v93, v99
	v_mul_f32_e32 v93, 0xbfb8aa3b, v94
	v_exp_f32_e32 v93, v93
	v_mul_f32_e32 v98, 0xbfb8aa3b, v95
	v_exp_f32_e32 v98, v98
	v_mul_f32_e32 v85, v85, v92
	v_add_f32_e32 v92, 1.0, v93
	v_rcp_f32_e32 v92, v92
	v_lshl_add_u64 v[112:113], v[112:113], 0, v[148:149]
	v_add_f32_e32 v93, 1.0, v98
	global_store_dwordx4 v[112:113], v[100:103], off
	v_rcp_f32_e32 v93, v93
	v_cvt_pk_bf16_f32 v84, v84, v85
	v_mul_f32_e32 v85, v94, v92
	v_mul_f32_e32 v92, 0xbfb8aa3b, v88
	v_exp_f32_e32 v92, v92
	v_mul_f32_e32 v85, v86, v85
	v_mul_f32_e32 v86, v95, v93
	v_mul_f32_e32 v93, 0xbfb8aa3b, v89
	v_exp_f32_e32 v93, v93
	v_mul_f32_e32 v86, v87, v86
	v_add_f32_e32 v87, 1.0, v92
	v_rcp_f32_e32 v87, v87
	v_add_f32_e32 v92, 1.0, v93
	v_rcp_f32_e32 v92, v92
	v_cvt_pk_bf16_f32 v85, v85, v86
	v_mul_f32_e32 v86, v88, v87
	v_mul_f32_e32 v87, 0xbfb8aa3b, v90
	v_exp_f32_e32 v87, v87
	v_mul_f32_e32 v88, 0xbfb8aa3b, v91
	v_exp_f32_e32 v88, v88
	v_mul_f32_e32 v80, v80, v86
	v_mul_f32_e32 v86, v89, v92
	v_mul_f32_e32 v81, v81, v86
	v_add_f32_e32 v86, 1.0, v87
	v_rcp_f32_e32 v87, v86
	v_add_f32_e32 v86, 1.0, v88
	v_rcp_f32_e32 v88, v86
	v_cvt_pk_bf16_f32 v86, v80, v81
	v_mul_f32_e32 v80, v90, v87
	v_mul_f32_e32 v80, v82, v80
	v_mul_f32_e32 v81, v91, v88
	v_mul_f32_e32 v81, v83, v81
	v_cvt_pk_bf16_f32 v87, v80, v81
	v_mul_f32_e32 v81, 0xbfb8aa3b, v76
	v_exp_f32_e32 v82, v81
	v_mul_f32_e32 v81, 0xbfb8aa3b, v77
	v_exp_f32_e32 v83, v81
	v_or_b32_e32 v96, 32, v156
	v_add_f32_e32 v82, 1.0, v82
	v_rcp_f32_e32 v82, v82
	v_add_f32_e32 v83, 1.0, v83
	v_rcp_f32_e32 v83, v83
	v_mad_i64_i32 v[96:97], s[6:7], v96, s36, v[146:147]
	v_mul_f32_e32 v76, v76, v82
	v_mul_f32_e32 v68, v68, v76
	v_mul_f32_e32 v76, v77, v83
	v_mul_f32_e32 v77, 0xbfb8aa3b, v78
	v_exp_f32_e32 v77, v77
	v_mul_f32_e32 v82, 0xbfb8aa3b, v79
	v_exp_f32_e32 v82, v82
	v_mul_f32_e32 v69, v69, v76
	v_add_f32_e32 v76, 1.0, v77
	v_rcp_f32_e32 v76, v76
	v_lshl_add_u64 v[96:97], v[96:97], 0, v[148:149]
	v_add_f32_e32 v77, 1.0, v82
	global_store_dwordx4 v[96:97], v[84:87], off
	v_rcp_f32_e32 v77, v77
	v_cvt_pk_bf16_f32 v68, v68, v69
	v_mul_f32_e32 v69, v78, v76
	v_mul_f32_e32 v76, 0xbfb8aa3b, v72
	v_exp_f32_e32 v76, v76
	v_mul_f32_e32 v69, v70, v69
	v_mul_f32_e32 v70, v79, v77
	v_mul_f32_e32 v77, 0xbfb8aa3b, v73
	v_exp_f32_e32 v77, v77
	v_mul_f32_e32 v70, v71, v70
	v_add_f32_e32 v71, 1.0, v76
	v_rcp_f32_e32 v71, v71
	v_add_f32_e32 v76, 1.0, v77
	v_rcp_f32_e32 v76, v76
	v_cvt_pk_bf16_f32 v69, v69, v70
	v_mul_f32_e32 v70, v72, v71
	v_mul_f32_e32 v71, 0xbfb8aa3b, v74
	v_exp_f32_e32 v71, v71
	v_mul_f32_e32 v72, 0xbfb8aa3b, v75
	v_exp_f32_e32 v72, v72
	v_mul_f32_e32 v64, v64, v70
	v_mul_f32_e32 v70, v73, v76
	v_mul_f32_e32 v65, v65, v70
	v_add_f32_e32 v70, 1.0, v71
	v_rcp_f32_e32 v71, v70
	v_add_f32_e32 v70, 1.0, v72
	v_rcp_f32_e32 v72, v70
	v_cvt_pk_bf16_f32 v70, v64, v65
	v_mul_f32_e32 v64, v74, v71
	v_mul_f32_e32 v64, v66, v64
	v_mul_f32_e32 v65, v75, v72
	v_mul_f32_e32 v65, v67, v65
	v_cvt_pk_bf16_f32 v71, v64, v65
	v_mul_f32_e32 v65, 0xbfb8aa3b, v60
	v_exp_f32_e32 v66, v65
	v_mul_f32_e32 v65, 0xbfb8aa3b, v61
	v_exp_f32_e32 v67, v65
	v_or_b32_e32 v80, 48, v156
	v_add_f32_e32 v66, 1.0, v66
	v_rcp_f32_e32 v66, v66
	v_add_f32_e32 v67, 1.0, v67
	v_rcp_f32_e32 v67, v67
	v_mad_i64_i32 v[80:81], s[6:7], v80, s36, v[146:147]
	v_mul_f32_e32 v60, v60, v66
	v_mul_f32_e32 v52, v52, v60
	v_mul_f32_e32 v60, v61, v67
	v_mul_f32_e32 v61, 0xbfb8aa3b, v62
	v_exp_f32_e32 v61, v61
	v_mul_f32_e32 v66, 0xbfb8aa3b, v63
	v_exp_f32_e32 v66, v66
	v_mul_f32_e32 v53, v53, v60
	v_add_f32_e32 v60, 1.0, v61
	v_rcp_f32_e32 v60, v60
	v_lshl_add_u64 v[80:81], v[80:81], 0, v[148:149]
	v_add_f32_e32 v61, 1.0, v66
	global_store_dwordx4 v[80:81], v[68:71], off
	v_rcp_f32_e32 v61, v61
	v_cvt_pk_bf16_f32 v52, v52, v53
	v_mul_f32_e32 v53, v62, v60
	v_mul_f32_e32 v60, 0xbfb8aa3b, v56
	v_exp_f32_e32 v60, v60
	v_mul_f32_e32 v53, v54, v53
	v_mul_f32_e32 v54, v63, v61
	v_mul_f32_e32 v61, 0xbfb8aa3b, v57
	v_exp_f32_e32 v61, v61
	v_mul_f32_e32 v54, v55, v54
	v_add_f32_e32 v55, 1.0, v60
	v_rcp_f32_e32 v55, v55
	v_add_f32_e32 v60, 1.0, v61
	v_rcp_f32_e32 v60, v60
	v_cvt_pk_bf16_f32 v53, v53, v54
	v_mul_f32_e32 v54, v56, v55
	v_mul_f32_e32 v55, 0xbfb8aa3b, v58
	v_exp_f32_e32 v55, v55
	v_mul_f32_e32 v56, 0xbfb8aa3b, v59
	v_exp_f32_e32 v56, v56
	v_mul_f32_e32 v48, v48, v54
	v_mul_f32_e32 v54, v57, v60
	v_mul_f32_e32 v49, v49, v54
	v_add_f32_e32 v54, 1.0, v55
	v_rcp_f32_e32 v55, v54
	v_add_f32_e32 v54, 1.0, v56
	v_rcp_f32_e32 v56, v54
	v_cvt_pk_bf16_f32 v54, v48, v49
	v_mul_f32_e32 v48, v58, v55
	v_mul_f32_e32 v48, v50, v48
	v_mul_f32_e32 v49, v59, v56
	v_mul_f32_e32 v49, v51, v49
	v_cvt_pk_bf16_f32 v55, v48, v49
	v_mul_f32_e32 v49, 0xbfb8aa3b, v44
	v_exp_f32_e32 v50, v49
	v_mul_f32_e32 v49, 0xbfb8aa3b, v45
	v_exp_f32_e32 v51, v49
	v_add_u32_e32 v64, 0x80, v156
	v_add_f32_e32 v50, 1.0, v50
	v_rcp_f32_e32 v50, v50
	v_add_f32_e32 v51, 1.0, v51
	v_rcp_f32_e32 v51, v51
	v_mad_i64_i32 v[64:65], s[6:7], v64, s36, v[146:147]
	v_mul_f32_e32 v44, v44, v50
	v_mul_f32_e32 v36, v36, v44
	v_mul_f32_e32 v44, v45, v51
	v_mul_f32_e32 v45, 0xbfb8aa3b, v46
	v_exp_f32_e32 v45, v45
	v_mul_f32_e32 v50, 0xbfb8aa3b, v47
	v_exp_f32_e32 v50, v50
	v_mul_f32_e32 v37, v37, v44
	v_add_f32_e32 v44, 1.0, v45
	v_rcp_f32_e32 v44, v44
	v_lshl_add_u64 v[64:65], v[64:65], 0, v[148:149]
	v_add_f32_e32 v45, 1.0, v50
	global_store_dwordx4 v[64:65], v[52:55], off
	v_rcp_f32_e32 v45, v45
	v_cvt_pk_bf16_f32 v36, v36, v37
	v_mul_f32_e32 v37, v46, v44
	v_mul_f32_e32 v44, 0xbfb8aa3b, v40
	v_exp_f32_e32 v44, v44
	v_mul_f32_e32 v37, v38, v37
	v_mul_f32_e32 v38, v47, v45
	v_mul_f32_e32 v45, 0xbfb8aa3b, v41
	v_exp_f32_e32 v45, v45
	v_mul_f32_e32 v38, v39, v38
	v_add_f32_e32 v39, 1.0, v44
	v_rcp_f32_e32 v39, v39
	v_add_f32_e32 v44, 1.0, v45
	v_rcp_f32_e32 v44, v44
	v_cvt_pk_bf16_f32 v37, v37, v38
	v_mul_f32_e32 v38, v40, v39
	v_mul_f32_e32 v39, 0xbfb8aa3b, v42
	v_exp_f32_e32 v39, v39
	v_mul_f32_e32 v40, 0xbfb8aa3b, v43
	v_exp_f32_e32 v40, v40
	v_mul_f32_e32 v32, v32, v38
	v_mul_f32_e32 v38, v41, v44
	v_mul_f32_e32 v33, v33, v38
	v_add_f32_e32 v38, 1.0, v39
	v_rcp_f32_e32 v39, v38
	v_add_f32_e32 v38, 1.0, v40
	v_rcp_f32_e32 v40, v38
	v_cvt_pk_bf16_f32 v38, v32, v33
	v_mul_f32_e32 v32, v42, v39
	v_mul_f32_e32 v32, v34, v32
	v_mul_f32_e32 v33, v43, v40
	v_mul_f32_e32 v33, v35, v33
	v_cvt_pk_bf16_f32 v39, v32, v33
	v_mul_f32_e32 v33, 0xbfb8aa3b, v28
	v_exp_f32_e32 v34, v33
	v_mul_f32_e32 v33, 0xbfb8aa3b, v29
	v_exp_f32_e32 v35, v33
	v_add_u32_e32 v48, 0x90, v156
	v_add_f32_e32 v34, 1.0, v34
	v_rcp_f32_e32 v34, v34
	v_add_f32_e32 v35, 1.0, v35
	v_rcp_f32_e32 v35, v35
	v_mad_i64_i32 v[48:49], s[6:7], v48, s36, v[146:147]
	v_mul_f32_e32 v28, v28, v34
	v_mul_f32_e32 v20, v20, v28
	v_mul_f32_e32 v28, v29, v35
	v_mul_f32_e32 v29, 0xbfb8aa3b, v30
	v_exp_f32_e32 v29, v29
	v_mul_f32_e32 v34, 0xbfb8aa3b, v31
	v_exp_f32_e32 v34, v34
	v_mul_f32_e32 v21, v21, v28
	v_add_f32_e32 v28, 1.0, v29
	v_rcp_f32_e32 v28, v28
	v_lshl_add_u64 v[48:49], v[48:49], 0, v[148:149]
	v_add_f32_e32 v29, 1.0, v34
	global_store_dwordx4 v[48:49], v[36:39], off
	v_rcp_f32_e32 v29, v29
	v_cvt_pk_bf16_f32 v20, v20, v21
	v_mul_f32_e32 v21, v30, v28
	v_mul_f32_e32 v28, 0xbfb8aa3b, v24
	v_exp_f32_e32 v28, v28
	v_mul_f32_e32 v21, v22, v21
	v_mul_f32_e32 v22, v31, v29
	v_mul_f32_e32 v29, 0xbfb8aa3b, v25
	v_exp_f32_e32 v29, v29
	v_mul_f32_e32 v22, v23, v22
	v_add_f32_e32 v23, 1.0, v28
	v_rcp_f32_e32 v23, v23
	v_add_f32_e32 v28, 1.0, v29
	v_rcp_f32_e32 v28, v28
	v_cvt_pk_bf16_f32 v21, v21, v22
	v_mul_f32_e32 v22, v24, v23
	v_mul_f32_e32 v23, 0xbfb8aa3b, v26
	v_exp_f32_e32 v23, v23
	v_mul_f32_e32 v24, 0xbfb8aa3b, v27
	v_exp_f32_e32 v24, v24
	v_mul_f32_e32 v16, v16, v22
	v_mul_f32_e32 v22, v25, v28
	v_mul_f32_e32 v17, v17, v22
	v_add_f32_e32 v22, 1.0, v23
	v_rcp_f32_e32 v23, v22
	v_add_f32_e32 v22, 1.0, v24
	v_rcp_f32_e32 v24, v22
	v_cvt_pk_bf16_f32 v22, v16, v17
	v_mul_f32_e32 v16, v26, v23
	v_mul_f32_e32 v16, v18, v16
	v_mul_f32_e32 v17, v27, v24
	v_mul_f32_e32 v17, v19, v17
	v_cvt_pk_bf16_f32 v23, v16, v17
	v_mul_f32_e32 v17, 0xbfb8aa3b, v12
	v_exp_f32_e32 v18, v17
	v_mul_f32_e32 v17, 0xbfb8aa3b, v13
	v_exp_f32_e32 v19, v17
	v_add_u32_e32 v32, 0xa0, v156
	v_add_f32_e32 v18, 1.0, v18
	v_rcp_f32_e32 v18, v18
	v_add_f32_e32 v19, 1.0, v19
	v_rcp_f32_e32 v19, v19
	v_mad_i64_i32 v[32:33], s[6:7], v32, s36, v[146:147]
	v_mul_f32_e32 v12, v12, v18
	v_mul_f32_e32 v4, v4, v12
	v_mul_f32_e32 v12, v13, v19
	v_mul_f32_e32 v13, 0xbfb8aa3b, v14
	v_exp_f32_e32 v13, v13
	v_mul_f32_e32 v18, 0xbfb8aa3b, v15
	v_exp_f32_e32 v18, v18
	v_mul_f32_e32 v5, v5, v12
	v_add_f32_e32 v12, 1.0, v13
	v_rcp_f32_e32 v12, v12
	v_lshl_add_u64 v[32:33], v[32:33], 0, v[148:149]
	v_add_f32_e32 v13, 1.0, v18
	global_store_dwordx4 v[32:33], v[20:23], off
	v_rcp_f32_e32 v13, v13
	v_cvt_pk_bf16_f32 v4, v4, v5
	v_mul_f32_e32 v5, v14, v12
	v_mul_f32_e32 v12, 0xbfb8aa3b, v8
	v_exp_f32_e32 v12, v12
	v_mul_f32_e32 v5, v6, v5
	v_mul_f32_e32 v6, v15, v13
	v_mul_f32_e32 v13, 0xbfb8aa3b, v9
	v_exp_f32_e32 v13, v13
	v_mul_f32_e32 v6, v7, v6
	v_add_f32_e32 v7, 1.0, v12
	v_rcp_f32_e32 v7, v7
	v_add_f32_e32 v12, 1.0, v13
	v_rcp_f32_e32 v12, v12
	v_cvt_pk_bf16_f32 v5, v5, v6
	v_mul_f32_e32 v6, v8, v7
	v_mul_f32_e32 v7, 0xbfb8aa3b, v10
	v_exp_f32_e32 v7, v7
	v_mul_f32_e32 v8, 0xbfb8aa3b, v11
	v_exp_f32_e32 v8, v8
	v_mul_f32_e32 v0, v0, v6
	v_mul_f32_e32 v6, v9, v12
	v_mul_f32_e32 v1, v1, v6
	v_add_f32_e32 v6, 1.0, v7
	v_rcp_f32_e32 v7, v6
	v_add_f32_e32 v6, 1.0, v8
	v_rcp_f32_e32 v8, v6
	v_add_u32_e32 v16, 0xb0, v156
	v_mad_i64_i32 v[16:17], s[6:7], v16, s36, v[146:147]
	v_lshl_add_u64 v[16:17], v[16:17], 0, v[148:149]
	v_cvt_pk_bf16_f32 v6, v0, v1
	v_mul_f32_e32 v0, v10, v7
	v_mul_f32_e32 v1, v11, v8
	s_andn2_b64 vcc, exec, s[0:1]
	s_mov_b64 s[0:1], -1
	v_mul_f32_e32 v0, v2, v0
	v_mul_f32_e32 v1, v3, v1
	v_cvt_pk_bf16_f32 v7, v0, v1
	global_store_dwordx4 v[16:17], v[4:7], off
	s_cmp_lt_i32 s58, 64
	s_cbranch_scc1 .Lsd3_e
	s_add_u32 s99, s99, 1
	s_waitcnt vmcnt(0)

.Lsd11_x:
	v_mul_f32_e32 v157, 0xbfb8aa3b, v124
	v_exp_f32_e32 v157, v157
	v_mul_f32_e32 v160, 0xbfb8aa3b, v125
	v_exp_f32_e32 v160, v160
	v_lshl_or_b32 v148, s54, 7, v152
	v_add_f32_e32 v157, 1.0, v157
	v_rcp_f32_e32 v157, v157
	v_add_f32_e32 v160, 1.0, v160
	v_rcp_f32_e32 v160, v160
	v_lshl_add_u32 v156, s36, 8, v150
	v_mul_f32_e32 v124, v124, v157
	v_mul_f32_e32 v116, v116, v124
	v_mul_f32_e32 v124, v125, v160
	v_mul_f32_e32 v125, 0xbfb8aa3b, v126
	v_exp_f32_e32 v125, v125
	v_mul_f32_e32 v157, 0xbfb8aa3b, v127
	v_exp_f32_e32 v157, v157
	v_mul_f32_e32 v117, v117, v124
	v_add_f32_e32 v124, 1.0, v125
	v_rcp_f32_e32 v124, v124
	v_add_f32_e32 v125, 1.0, v157
	v_rcp_f32_e32 v125, v125
	v_cvt_pk_bf16_f32 v116, v116, v117
	v_mul_f32_e32 v117, v126, v124
	v_mul_f32_e32 v124, 0xbfb8aa3b, v120
	v_exp_f32_e32 v124, v124
	v_mul_f32_e32 v117, v118, v117
	v_mul_f32_e32 v118, v127, v125
	v_mul_f32_e32 v125, 0xbfb8aa3b, v121
	v_exp_f32_e32 v125, v125
	v_mul_f32_e32 v118, v119, v118
	v_add_f32_e32 v119, 1.0, v124
	v_rcp_f32_e32 v119, v119
	v_add_f32_e32 v124, 1.0, v125
	v_rcp_f32_e32 v124, v124
	v_cvt_pk_bf16_f32 v117, v117, v118
	v_mul_f32_e32 v118, v120, v119
	v_mul_f32_e32 v119, 0xbfb8aa3b, v122
	v_exp_f32_e32 v119, v119
	v_mul_f32_e32 v120, 0xbfb8aa3b, v123
	v_exp_f32_e32 v120, v120
	v_mul_f32_e32 v112, v112, v118
	v_mul_f32_e32 v118, v121, v124
	v_mul_f32_e32 v113, v113, v118
	v_add_f32_e32 v118, 1.0, v119
	v_rcp_f32_e32 v119, v118
	v_add_f32_e32 v118, 1.0, v120
	v_rcp_f32_e32 v120, v118
	v_cvt_pk_bf16_f32 v118, v112, v113
	v_mul_f32_e32 v112, v122, v119
	v_mul_f32_e32 v112, v114, v112
	v_mul_f32_e32 v113, v123, v120
	v_mul_f32_e32 v113, v115, v113
	v_cvt_pk_bf16_f32 v119, v112, v113
	v_mul_f32_e32 v113, 0xbfb8aa3b, v108
	v_exp_f32_e32 v114, v113
	v_mul_f32_e32 v113, 0xbfb8aa3b, v109
	v_exp_f32_e32 v115, v113
	v_ashrrev_i32_e32 v149, 31, v148
	v_add_f32_e32 v114, 1.0, v114
	v_rcp_f32_e32 v114, v114
	v_add_f32_e32 v115, 1.0, v115
	v_rcp_f32_e32 v115, v115
	v_mov_b64_e32 v[146:147], s[18:19]
	v_mul_f32_e32 v108, v108, v114
	v_mul_f32_e32 v100, v100, v108
	v_mul_f32_e32 v108, v109, v115
	v_mul_f32_e32 v109, 0xbfb8aa3b, v110
	v_exp_f32_e32 v109, v109
	v_mul_f32_e32 v114, 0xbfb8aa3b, v111
	v_exp_f32_e32 v114, v114
	v_mul_f32_e32 v101, v101, v108
	v_add_f32_e32 v108, 1.0, v109
	v_rcp_f32_e32 v108, v108
	v_mad_i64_i32 v[158:159], s[6:7], v156, s53, v[146:147]
	v_lshlrev_b64 v[148:149], 1, v[148:149]
	v_lshl_add_u64 v[158:159], v[158:159], 0, v[148:149]
	v_add_f32_e32 v109, 1.0, v114
	global_store_dwordx4 v[158:159], v[116:119], off
	v_rcp_f32_e32 v109, v109
	v_cvt_pk_bf16_f32 v100, v100, v101
	v_mul_f32_e32 v101, v110, v108
	v_mul_f32_e32 v108, 0xbfb8aa3b, v104
	v_exp_f32_e32 v108, v108
	v_mul_f32_e32 v101, v102, v101
	v_mul_f32_e32 v102, v111, v109
	v_mul_f32_e32 v109, 0xbfb8aa3b, v105
	v_exp_f32_e32 v109, v109
	v_mul_f32_e32 v102, v103, v102
	v_add_f32_e32 v103, 1.0, v108
	v_rcp_f32_e32 v103, v103
	v_add_f32_e32 v108, 1.0, v109
	v_rcp_f32_e32 v108, v108
	v_cvt_pk_bf16_f32 v101, v101, v102
	v_mul_f32_e32 v102, v104, v103
	v_mul_f32_e32 v103, 0xbfb8aa3b, v106
	v_exp_f32_e32 v103, v103
	v_mul_f32_e32 v104, 0xbfb8aa3b, v107
	v_exp_f32_e32 v104, v104
	v_mul_f32_e32 v96, v96, v102
	v_mul_f32_e32 v102, v105, v108
	v_mul_f32_e32 v97, v97, v102
	v_add_f32_e32 v102, 1.0, v103
	v_rcp_f32_e32 v103, v102
	v_add_f32_e32 v102, 1.0, v104
	v_rcp_f32_e32 v104, v102
	v_cvt_pk_bf16_f32 v102, v96, v97
	v_mul_f32_e32 v96, v106, v103
	v_mul_f32_e32 v96, v98, v96
	v_mul_f32_e32 v97, v107, v104
	v_mul_f32_e32 v97, v99, v97
	v_cvt_pk_bf16_f32 v103, v96, v97
	v_mul_f32_e32 v97, 0xbfb8aa3b, v92
	v_exp_f32_e32 v98, v97
	v_mul_f32_e32 v97, 0xbfb8aa3b, v93
	v_exp_f32_e32 v99, v97
	v_or_b32_e32 v112, 16, v156
	v_add_f32_e32 v98, 1.0, v98
	v_rcp_f32_e32 v98, v98
	v_add_f32_e32 v99, 1.0, v99
	v_rcp_f32_e32 v99, v99
	v_mad_i64_i32 v[112:113], s[6:7], v112, s53, v[146:147]
	v_mul_f32_e32 v92, v92, v98
	v_mul_f32_e32 v84, v84, v92
	v_mul_f32_e32 v92, v93, v99
	v_mul_f32_e32 v93, 0xbfb8aa3b, v94
	v_exp_f32_e32 v93, v93
	v_mul_f32_e32 v98, 0xbfb8aa3b, v95
	v_exp_f32_e32 v98, v98
	v_mul_f32_e32 v85, v85, v92
	v_add_f32_e32 v92, 1.0, v93
	v_rcp_f32_e32 v92, v92
	v_lshl_add_u64 v[112:113], v[112:113], 0, v[148:149]
	v_add_f32_e32 v93, 1.0, v98
	global_store_dwordx4 v[112:113], v[100:103], off
	v_rcp_f32_e32 v93, v93
	v_cvt_pk_bf16_f32 v84, v84, v85
	v_mul_f32_e32 v85, v94, v92
	v_mul_f32_e32 v92, 0xbfb8aa3b, v88
	v_exp_f32_e32 v92, v92
	v_mul_f32_e32 v85, v86, v85
	v_mul_f32_e32 v86, v95, v93
	v_mul_f32_e32 v93, 0xbfb8aa3b, v89
	v_exp_f32_e32 v93, v93
	v_mul_f32_e32 v86, v87, v86
	v_add_f32_e32 v87, 1.0, v92
	v_rcp_f32_e32 v87, v87
	v_add_f32_e32 v92, 1.0, v93
	v_rcp_f32_e32 v92, v92
	v_cvt_pk_bf16_f32 v85, v85, v86
	v_mul_f32_e32 v86, v88, v87
	v_mul_f32_e32 v87, 0xbfb8aa3b, v90
	v_exp_f32_e32 v87, v87
	v_mul_f32_e32 v88, 0xbfb8aa3b, v91
	v_exp_f32_e32 v88, v88
	v_mul_f32_e32 v80, v80, v86
	v_mul_f32_e32 v86, v89, v92
	v_mul_f32_e32 v81, v81, v86
	v_add_f32_e32 v86, 1.0, v87
	v_rcp_f32_e32 v87, v86
	v_add_f32_e32 v86, 1.0, v88
	v_rcp_f32_e32 v88, v86
	v_cvt_pk_bf16_f32 v86, v80, v81
	v_mul_f32_e32 v80, v90, v87
	v_mul_f32_e32 v80, v82, v80
	v_mul_f32_e32 v81, v91, v88
	v_mul_f32_e32 v81, v83, v81
	v_cvt_pk_bf16_f32 v87, v80, v81
	v_mul_f32_e32 v81, 0xbfb8aa3b, v76
	v_exp_f32_e32 v82, v81
	v_mul_f32_e32 v81, 0xbfb8aa3b, v77
	v_exp_f32_e32 v83, v81
	v_or_b32_e32 v96, 32, v156
	v_add_f32_e32 v82, 1.0, v82
	v_rcp_f32_e32 v82, v82
	v_add_f32_e32 v83, 1.0, v83
	v_rcp_f32_e32 v83, v83
	v_mad_i64_i32 v[96:97], s[6:7], v96, s53, v[146:147]
	v_mul_f32_e32 v76, v76, v82
	v_mul_f32_e32 v68, v68, v76
	v_mul_f32_e32 v76, v77, v83
	v_mul_f32_e32 v77, 0xbfb8aa3b, v78
	v_exp_f32_e32 v77, v77
	v_mul_f32_e32 v82, 0xbfb8aa3b, v79
	v_exp_f32_e32 v82, v82
	v_mul_f32_e32 v69, v69, v76
	v_add_f32_e32 v76, 1.0, v77
	v_rcp_f32_e32 v76, v76
	v_lshl_add_u64 v[96:97], v[96:97], 0, v[148:149]
	v_add_f32_e32 v77, 1.0, v82
	global_store_dwordx4 v[96:97], v[84:87], off
	v_rcp_f32_e32 v77, v77
	v_cvt_pk_bf16_f32 v68, v68, v69
	v_mul_f32_e32 v69, v78, v76
	v_mul_f32_e32 v76, 0xbfb8aa3b, v72
	v_exp_f32_e32 v76, v76
	v_mul_f32_e32 v69, v70, v69
	v_mul_f32_e32 v70, v79, v77
	v_mul_f32_e32 v77, 0xbfb8aa3b, v73
	v_exp_f32_e32 v77, v77
	v_mul_f32_e32 v70, v71, v70
	v_add_f32_e32 v71, 1.0, v76
	v_rcp_f32_e32 v71, v71
	v_add_f32_e32 v76, 1.0, v77
	v_rcp_f32_e32 v76, v76
	v_cvt_pk_bf16_f32 v69, v69, v70
	v_mul_f32_e32 v70, v72, v71
	v_mul_f32_e32 v71, 0xbfb8aa3b, v74
	v_exp_f32_e32 v71, v71
	v_mul_f32_e32 v72, 0xbfb8aa3b, v75
	v_exp_f32_e32 v72, v72
	v_mul_f32_e32 v64, v64, v70
	v_mul_f32_e32 v70, v73, v76
	v_mul_f32_e32 v65, v65, v70
	v_add_f32_e32 v70, 1.0, v71
	v_rcp_f32_e32 v71, v70
	v_add_f32_e32 v70, 1.0, v72
	v_rcp_f32_e32 v72, v70
	v_cvt_pk_bf16_f32 v70, v64, v65
	v_mul_f32_e32 v64, v74, v71
	v_mul_f32_e32 v64, v66, v64
	v_mul_f32_e32 v65, v75, v72
	v_mul_f32_e32 v65, v67, v65
	v_cvt_pk_bf16_f32 v71, v64, v65
	v_mul_f32_e32 v65, 0xbfb8aa3b, v60
	v_exp_f32_e32 v66, v65
	v_mul_f32_e32 v65, 0xbfb8aa3b, v61
	v_exp_f32_e32 v67, v65
	v_or_b32_e32 v80, 48, v156
	v_add_f32_e32 v66, 1.0, v66
	v_rcp_f32_e32 v66, v66
	v_add_f32_e32 v67, 1.0, v67
	v_rcp_f32_e32 v67, v67
	v_mad_i64_i32 v[80:81], s[6:7], v80, s53, v[146:147]
	v_mul_f32_e32 v60, v60, v66
	v_mul_f32_e32 v52, v52, v60
	v_mul_f32_e32 v60, v61, v67
	v_mul_f32_e32 v61, 0xbfb8aa3b, v62
	v_exp_f32_e32 v61, v61
	v_mul_f32_e32 v66, 0xbfb8aa3b, v63
	v_exp_f32_e32 v66, v66
	v_mul_f32_e32 v53, v53, v60
	v_add_f32_e32 v60, 1.0, v61
	v_rcp_f32_e32 v60, v60
	v_lshl_add_u64 v[80:81], v[80:81], 0, v[148:149]
	v_add_f32_e32 v61, 1.0, v66
	global_store_dwordx4 v[80:81], v[68:71], off
	v_rcp_f32_e32 v61, v61
	v_cvt_pk_bf16_f32 v52, v52, v53
	v_mul_f32_e32 v53, v62, v60
	v_mul_f32_e32 v60, 0xbfb8aa3b, v56
	v_exp_f32_e32 v60, v60
	v_mul_f32_e32 v53, v54, v53
	v_mul_f32_e32 v54, v63, v61
	v_mul_f32_e32 v61, 0xbfb8aa3b, v57
	v_exp_f32_e32 v61, v61
	v_mul_f32_e32 v54, v55, v54
	v_add_f32_e32 v55, 1.0, v60
	v_rcp_f32_e32 v55, v55
	v_add_f32_e32 v60, 1.0, v61
	v_rcp_f32_e32 v60, v60
	v_cvt_pk_bf16_f32 v53, v53, v54
	v_mul_f32_e32 v54, v56, v55
	v_mul_f32_e32 v55, 0xbfb8aa3b, v58
	v_exp_f32_e32 v55, v55
	v_mul_f32_e32 v56, 0xbfb8aa3b, v59
	v_exp_f32_e32 v56, v56
	v_mul_f32_e32 v48, v48, v54
	v_mul_f32_e32 v54, v57, v60
	v_mul_f32_e32 v49, v49, v54
	v_add_f32_e32 v54, 1.0, v55
	v_rcp_f32_e32 v55, v54
	v_add_f32_e32 v54, 1.0, v56
	v_rcp_f32_e32 v56, v54
	v_cvt_pk_bf16_f32 v54, v48, v49
	v_mul_f32_e32 v48, v58, v55
	v_mul_f32_e32 v48, v50, v48
	v_mul_f32_e32 v49, v59, v56
	v_mul_f32_e32 v49, v51, v49
	v_cvt_pk_bf16_f32 v55, v48, v49
	v_mul_f32_e32 v49, 0xbfb8aa3b, v44
	v_exp_f32_e32 v50, v49
	v_mul_f32_e32 v49, 0xbfb8aa3b, v45
	v_exp_f32_e32 v51, v49
	v_add_u32_e32 v64, 0x80, v156
	v_add_f32_e32 v50, 1.0, v50
	v_rcp_f32_e32 v50, v50
	v_add_f32_e32 v51, 1.0, v51
	v_rcp_f32_e32 v51, v51
	v_mad_i64_i32 v[64:65], s[6:7], v64, s53, v[146:147]
	v_mul_f32_e32 v44, v44, v50
	v_mul_f32_e32 v36, v36, v44
	v_mul_f32_e32 v44, v45, v51
	v_mul_f32_e32 v45, 0xbfb8aa3b, v46
	v_exp_f32_e32 v45, v45
	v_mul_f32_e32 v50, 0xbfb8aa3b, v47
	v_exp_f32_e32 v50, v50
	v_mul_f32_e32 v37, v37, v44
	v_add_f32_e32 v44, 1.0, v45
	v_rcp_f32_e32 v44, v44
	v_lshl_add_u64 v[64:65], v[64:65], 0, v[148:149]
	v_add_f32_e32 v45, 1.0, v50
	global_store_dwordx4 v[64:65], v[52:55], off
	v_rcp_f32_e32 v45, v45
	v_cvt_pk_bf16_f32 v36, v36, v37
	v_mul_f32_e32 v37, v46, v44
	v_mul_f32_e32 v44, 0xbfb8aa3b, v40
	v_exp_f32_e32 v44, v44
	v_mul_f32_e32 v37, v38, v37
	v_mul_f32_e32 v38, v47, v45
	v_mul_f32_e32 v45, 0xbfb8aa3b, v41
	v_exp_f32_e32 v45, v45
	v_mul_f32_e32 v38, v39, v38
	v_add_f32_e32 v39, 1.0, v44
	v_rcp_f32_e32 v39, v39
	v_add_f32_e32 v44, 1.0, v45
	v_rcp_f32_e32 v44, v44
	v_cvt_pk_bf16_f32 v37, v37, v38
	v_mul_f32_e32 v38, v40, v39
	v_mul_f32_e32 v39, 0xbfb8aa3b, v42
	v_exp_f32_e32 v39, v39
	v_mul_f32_e32 v40, 0xbfb8aa3b, v43
	v_exp_f32_e32 v40, v40
	v_mul_f32_e32 v32, v32, v38
	v_mul_f32_e32 v38, v41, v44
	v_mul_f32_e32 v33, v33, v38
	v_add_f32_e32 v38, 1.0, v39
	v_rcp_f32_e32 v39, v38
	v_add_f32_e32 v38, 1.0, v40
	v_rcp_f32_e32 v40, v38
	v_cvt_pk_bf16_f32 v38, v32, v33
	v_mul_f32_e32 v32, v42, v39
	v_mul_f32_e32 v32, v34, v32
	v_mul_f32_e32 v33, v43, v40
	v_mul_f32_e32 v33, v35, v33
	v_cvt_pk_bf16_f32 v39, v32, v33
	v_mul_f32_e32 v33, 0xbfb8aa3b, v28
	v_exp_f32_e32 v34, v33
	v_mul_f32_e32 v33, 0xbfb8aa3b, v29
	v_exp_f32_e32 v35, v33
	v_add_u32_e32 v48, 0x90, v156
	v_add_f32_e32 v34, 1.0, v34
	v_rcp_f32_e32 v34, v34
	v_add_f32_e32 v35, 1.0, v35
	v_rcp_f32_e32 v35, v35
	v_mad_i64_i32 v[48:49], s[6:7], v48, s53, v[146:147]
	v_mul_f32_e32 v28, v28, v34
	v_mul_f32_e32 v20, v20, v28
	v_mul_f32_e32 v28, v29, v35
	v_mul_f32_e32 v29, 0xbfb8aa3b, v30
	v_exp_f32_e32 v29, v29
	v_mul_f32_e32 v34, 0xbfb8aa3b, v31
	v_exp_f32_e32 v34, v34
	v_mul_f32_e32 v21, v21, v28
	v_add_f32_e32 v28, 1.0, v29
	v_rcp_f32_e32 v28, v28
	v_lshl_add_u64 v[48:49], v[48:49], 0, v[148:149]
	v_add_f32_e32 v29, 1.0, v34
	global_store_dwordx4 v[48:49], v[36:39], off
	v_rcp_f32_e32 v29, v29
	v_cvt_pk_bf16_f32 v20, v20, v21
	v_mul_f32_e32 v21, v30, v28
	v_mul_f32_e32 v28, 0xbfb8aa3b, v24
	v_exp_f32_e32 v28, v28
	v_mul_f32_e32 v21, v22, v21
	v_mul_f32_e32 v22, v31, v29
	v_mul_f32_e32 v29, 0xbfb8aa3b, v25
	v_exp_f32_e32 v29, v29
	v_mul_f32_e32 v22, v23, v22
	v_add_f32_e32 v23, 1.0, v28
	v_rcp_f32_e32 v23, v23
	v_add_f32_e32 v28, 1.0, v29
	v_rcp_f32_e32 v28, v28
	v_cvt_pk_bf16_f32 v21, v21, v22
	v_mul_f32_e32 v22, v24, v23
	v_mul_f32_e32 v23, 0xbfb8aa3b, v26
	v_exp_f32_e32 v23, v23
	v_mul_f32_e32 v24, 0xbfb8aa3b, v27
	v_exp_f32_e32 v24, v24
	v_mul_f32_e32 v16, v16, v22
	v_mul_f32_e32 v22, v25, v28
	v_mul_f32_e32 v17, v17, v22
	v_add_f32_e32 v22, 1.0, v23
	v_rcp_f32_e32 v23, v22
	v_add_f32_e32 v22, 1.0, v24
	v_rcp_f32_e32 v24, v22
	v_cvt_pk_bf16_f32 v22, v16, v17
	v_mul_f32_e32 v16, v26, v23
	v_mul_f32_e32 v16, v18, v16
	v_mul_f32_e32 v17, v27, v24
	v_mul_f32_e32 v17, v19, v17
	v_cvt_pk_bf16_f32 v23, v16, v17
	v_mul_f32_e32 v17, 0xbfb8aa3b, v12
	v_exp_f32_e32 v18, v17
	v_mul_f32_e32 v17, 0xbfb8aa3b, v13
	v_exp_f32_e32 v19, v17
	v_add_u32_e32 v32, 0xa0, v156
	v_add_f32_e32 v18, 1.0, v18
	v_rcp_f32_e32 v18, v18
	v_add_f32_e32 v19, 1.0, v19
	v_rcp_f32_e32 v19, v19
	v_mad_i64_i32 v[32:33], s[6:7], v32, s53, v[146:147]
	v_mul_f32_e32 v12, v12, v18
	v_mul_f32_e32 v4, v4, v12
	v_mul_f32_e32 v12, v13, v19
	v_mul_f32_e32 v13, 0xbfb8aa3b, v14
	v_exp_f32_e32 v13, v13
	v_mul_f32_e32 v18, 0xbfb8aa3b, v15
	v_exp_f32_e32 v18, v18
	v_mul_f32_e32 v5, v5, v12
	v_add_f32_e32 v12, 1.0, v13
	v_rcp_f32_e32 v12, v12
	v_lshl_add_u64 v[32:33], v[32:33], 0, v[148:149]
	v_add_f32_e32 v13, 1.0, v18
	global_store_dwordx4 v[32:33], v[20:23], off
	v_rcp_f32_e32 v13, v13
	v_cvt_pk_bf16_f32 v4, v4, v5
	v_mul_f32_e32 v5, v14, v12
	v_mul_f32_e32 v12, 0xbfb8aa3b, v8
	v_exp_f32_e32 v12, v12
	v_mul_f32_e32 v5, v6, v5
	v_mul_f32_e32 v6, v15, v13
	v_mul_f32_e32 v13, 0xbfb8aa3b, v9
	v_exp_f32_e32 v13, v13
	v_mul_f32_e32 v6, v7, v6
	v_add_f32_e32 v7, 1.0, v12
	v_rcp_f32_e32 v7, v7
	v_add_f32_e32 v12, 1.0, v13
	v_rcp_f32_e32 v12, v12
	v_cvt_pk_bf16_f32 v5, v5, v6
	v_mul_f32_e32 v6, v8, v7
	v_mul_f32_e32 v7, 0xbfb8aa3b, v10
	v_exp_f32_e32 v7, v7
	v_mul_f32_e32 v8, 0xbfb8aa3b, v11
	v_exp_f32_e32 v8, v8
	v_mul_f32_e32 v0, v0, v6
	v_mul_f32_e32 v6, v9, v12
	v_mul_f32_e32 v1, v1, v6
	v_add_f32_e32 v6, 1.0, v7
	v_rcp_f32_e32 v7, v6
	v_add_f32_e32 v6, 1.0, v8
	v_rcp_f32_e32 v8, v6
	v_add_u32_e32 v16, 0xb0, v156
	v_mad_i64_i32 v[16:17], s[6:7], v16, s53, v[146:147]
	v_lshl_add_u64 v[16:17], v[16:17], 0, v[148:149]
	v_cvt_pk_bf16_f32 v6, v0, v1
	v_mul_f32_e32 v0, v10, v7
	v_mul_f32_e32 v1, v11, v8
	s_andn2_b64 vcc, exec, s[0:1]
	s_mov_b64 s[0:1], -1
	v_mul_f32_e32 v0, v2, v0
	v_mul_f32_e32 v1, v3, v1
	v_cvt_pk_bf16_f32 v7, v0, v1
	global_store_dwordx4 v[16:17], v[4:7], off
	s_cmp_lt_i32 s36, 64
	s_cbranch_scc1 .Lsd11_e
	s_add_u32 s99, s99, 1
	s_waitcnt vmcnt(0)
